# early-invalidate-in-splitK-exchange
# baseline (speedup 1.0000x reference)
.LBB0_448:
	s_or_b64 exec, exec, s[58:59]
	buffer_inv sc1
	s_mov_b32 s10, 0x400001
	s_branch .LBB0_450

.LBB0_450:
	global_load_dword v70, v133, s[52:53] sc1
	s_mov_b64 s[54:55], -1
	s_waitcnt vmcnt(0)
	v_cmp_lt_u32_e32 vcc, 7, v70
	s_cbranch_vccnz .LBB0_449
	s_sleep 2
	global_load_dword v70, v133, s[52:53] sc1
	s_waitcnt vmcnt(0)
	v_cmp_gt_u32_e32 vcc, 8, v70
	s_cbranch_vccz .LBB0_449
	s_sleep 2
	global_load_dword v70, v133, s[52:53] sc1
	s_waitcnt vmcnt(0)
	v_cmp_gt_u32_e32 vcc, 8, v70
	s_cbranch_vccz .LBB0_449
	s_sleep 2
	global_load_dword v70, v133, s[52:53] sc1
	s_waitcnt vmcnt(0)
	v_cmp_gt_u32_e32 vcc, 8, v70
	s_cbranch_vccz .LBB0_449
	s_sleep 2
	global_load_dword v70, v133, s[52:53] sc1
	s_waitcnt vmcnt(0)
	v_cmp_gt_u32_e32 vcc, 8, v70
	s_cbranch_vccz .LBB0_449
	s_add_i32 s10, s10, -5
	s_cmp_eq_u32 s10, 0
	s_cselect_b64 s[54:55], -1, 0
	s_sleep 2
	s_branch .LBB0_449
.LBB0_456:
	s_waitcnt vmcnt(0)
.LBB0_457:
	s_or_b64 exec, exec, s[46:47]
	s_ashr_i32 s37, s36, 31
	s_lshl_b64 s[36:37], s[36:37], 17
	s_lshl_b32 s10, s82, 1
	v_lshl_add_u64 v[70:71], v[138:139], 0, s[36:37]
	s_lshl_b64 s[36:37], s[10:11], 13
	v_lshl_add_u64 v[70:71], v[70:71], 0, s[36:37]
	v_add_co_u32_e32 v72, vcc, 0x2000, v70
	s_nop 1
	v_addc_co_u32_e32 v73, vcc, 0, v71, vcc
	s_barrier
	global_load_dwordx4 v[102:105], v[70:71], off
	global_load_dwordx4 v[98:101], v[72:73], off
	v_add_co_u32_e32 v72, vcc, 0x20000, v70
	s_lshl_b32 s10, s82, 5
	s_nop 0
	v_addc_co_u32_e32 v73, vcc, 0, v71, vcc
	v_add_co_u32_e32 v74, vcc, 0x22000, v70
	s_and_b32 s10, s10, 0x7fffff80
	s_nop 0
	v_addc_co_u32_e32 v75, vcc, 0, v71, vcc
	global_load_dwordx4 v[106:109], v[72:73], off
	global_load_dwordx4 v[94:97], v[74:75], off
	v_add_co_u32_e32 v72, vcc, 0x40000, v70
	v_add_u32_e32 v147, s10, v148
	s_nop 0
	v_addc_co_u32_e32 v73, vcc, 0, v71, vcc
	v_add_co_u32_e32 v74, vcc, 0x42000, v70
	s_lshl_b32 s10, s82, 4
	s_nop 0
	v_addc_co_u32_e32 v75, vcc, 0, v71, vcc
	global_load_dwordx4 v[110:113], v[72:73], off
	global_load_dwordx4 v[90:93], v[74:75], off
	v_add_co_u32_e32 v72, vcc, 0x60000, v70
	v_and_or_b32 v160, s10, 48, v147
	s_nop 0
	v_addc_co_u32_e32 v73, vcc, 0, v71, vcc
	v_add_co_u32_e32 v74, vcc, 0x62000, v70
	v_ashrrev_i32_e32 v161, 31, v160
	s_nop 0
	v_addc_co_u32_e32 v75, vcc, 0, v71, vcc
	global_load_dwordx4 v[114:117], v[72:73], off
	global_load_dwordx4 v[86:89], v[74:75], off
	v_add_co_u32_e32 v72, vcc, 0x80000, v70
	v_ashrrev_i32_e32 v147, 31, v146
	s_nop 0
	v_addc_co_u32_e32 v73, vcc, 0, v71, vcc
	v_add_co_u32_e32 v74, vcc, 0x82000, v70
	s_mov_b64 s[36:37], 0
	s_nop 0
	v_addc_co_u32_e32 v75, vcc, 0, v71, vcc
	global_load_dwordx4 v[118:121], v[72:73], off
	global_load_dwordx4 v[82:85], v[74:75], off
	v_add_co_u32_e32 v72, vcc, 0xa0000, v70
	s_waitcnt vmcnt(9)
	v_lshlrev_b32_e32 v162, 16, v102
	v_addc_co_u32_e32 v73, vcc, 0, v71, vcc
	v_add_co_u32_e32 v74, vcc, 0xa2000, v70
	v_and_b32_e32 v163, 0xffff0000, v102
	s_nop 0
	v_addc_co_u32_e32 v75, vcc, 0, v71, vcc
	global_load_dwordx4 v[122:125], v[72:73], off
	global_load_dwordx4 v[78:81], v[74:75], off
	v_add_co_u32_e32 v72, vcc, 0xc0000, v70
	v_lshlrev_b32_e32 v102, 16, v103
	s_nop 0
	v_addc_co_u32_e32 v73, vcc, 0, v71, vcc
	v_add_co_u32_e32 v74, vcc, 0xc2000, v70
	v_and_b32_e32 v103, 0xffff0000, v103
	s_nop 0
	v_addc_co_u32_e32 v75, vcc, 0, v71, vcc
	global_load_dwordx4 v[126:129], v[72:73], off
	s_nop 0
	global_load_dwordx4 v[74:77], v[74:75], off
	v_add_co_u32_e32 v72, vcc, 0xe0000, v70
	v_pk_add_f32 v[162:163], v[162:163], 0 op_sel_hi:[1,0]
	s_nop 0
	v_addc_co_u32_e32 v73, vcc, 0, v71, vcc
	v_add_co_u32_e32 v70, vcc, 0xe2000, v70
	v_pk_add_f32 v[102:103], v[102:103], 0 op_sel_hi:[1,0]
	s_nop 0
	v_addc_co_u32_e32 v71, vcc, 0, v71, vcc
	global_load_dwordx4 v[156:159], v[72:73], off
	s_nop 0
	global_load_dwordx4 v[70:73], v[70:71], off
	v_lshlrev_b32_e32 v164, 16, v104
	v_and_b32_e32 v165, 0xffff0000, v104
	v_lshlrev_b32_e32 v104, 16, v105
	v_and_b32_e32 v105, 0xffff0000, v105
	s_waitcnt vmcnt(13)
	v_lshlrev_b32_e32 v166, 16, v106
	v_and_b32_e32 v167, 0xffff0000, v106
	v_lshlrev_b32_e32 v106, 16, v107
	v_and_b32_e32 v107, 0xffff0000, v107
	v_pk_add_f32 v[164:165], v[164:165], 0 op_sel_hi:[1,0]
	v_pk_add_f32 v[104:105], v[104:105], 0 op_sel_hi:[1,0]
	v_pk_add_f32 v[102:103], v[102:103], v[106:107]
	v_pk_add_f32 v[106:107], v[162:163], v[166:167]
	v_lshlrev_b32_e32 v162, 16, v108
	v_and_b32_e32 v163, 0xffff0000, v108
	v_lshlrev_b32_e32 v108, 16, v109
	v_and_b32_e32 v109, 0xffff0000, v109
	v_pk_add_f32 v[104:105], v[104:105], v[108:109]
	v_pk_add_f32 v[108:109], v[164:165], v[162:163]
	s_waitcnt vmcnt(11)
	v_lshlrev_b32_e32 v162, 16, v110
	v_and_b32_e32 v163, 0xffff0000, v110
	v_lshlrev_b32_e32 v110, 16, v111
	v_and_b32_e32 v111, 0xffff0000, v111
	v_pk_add_f32 v[102:103], v[102:103], v[110:111]
	v_lshlrev_b32_e32 v110, 16, v112
	v_and_b32_e32 v111, 0xffff0000, v112
	v_lshlrev_b32_e32 v112, 16, v113
	v_and_b32_e32 v113, 0xffff0000, v113
	v_pk_add_f32 v[106:107], v[106:107], v[162:163]
	v_pk_add_f32 v[108:109], v[108:109], v[110:111]
	v_pk_add_f32 v[104:105], v[104:105], v[112:113]
	s_waitcnt vmcnt(9)
	v_lshlrev_b32_e32 v110, 16, v114
	v_and_b32_e32 v111, 0xffff0000, v114
	v_lshlrev_b32_e32 v112, 16, v115
	v_and_b32_e32 v113, 0xffff0000, v115
	v_pk_add_f32 v[102:103], v[102:103], v[112:113]
	v_pk_add_f32 v[106:107], v[106:107], v[110:111]
	v_lshlrev_b32_e32 v110, 16, v116
	v_and_b32_e32 v111, 0xffff0000, v116
	v_lshlrev_b32_e32 v112, 16, v117
	v_and_b32_e32 v113, 0xffff0000, v117
	v_pk_add_f32 v[104:105], v[104:105], v[112:113]
	v_pk_add_f32 v[108:109], v[108:109], v[110:111]
	s_waitcnt vmcnt(7)
	v_lshlrev_b32_e32 v110, 16, v118
	v_and_b32_e32 v111, 0xffff0000, v118
	v_lshlrev_b32_e32 v112, 16, v119
	v_and_b32_e32 v113, 0xffff0000, v119
	v_pk_add_f32 v[106:107], v[106:107], v[110:111]
	v_pk_add_f32 v[102:103], v[102:103], v[112:113]
	v_lshlrev_b32_e32 v110, 16, v120
	v_and_b32_e32 v111, 0xffff0000, v120
	v_lshlrev_b32_e32 v112, 16, v121
	v_and_b32_e32 v113, 0xffff0000, v121
	v_pk_add_f32 v[108:109], v[108:109], v[110:111]
	v_pk_add_f32 v[104:105], v[104:105], v[112:113]
	s_waitcnt vmcnt(5)
	v_lshlrev_b32_e32 v110, 16, v122
	v_and_b32_e32 v111, 0xffff0000, v122
	v_lshlrev_b32_e32 v112, 16, v123
	v_and_b32_e32 v113, 0xffff0000, v123
	v_pk_add_f32 v[102:103], v[102:103], v[112:113]
	v_pk_add_f32 v[106:107], v[106:107], v[110:111]
	v_lshlrev_b32_e32 v110, 16, v124
	v_and_b32_e32 v111, 0xffff0000, v124
	v_lshlrev_b32_e32 v112, 16, v125
	v_and_b32_e32 v113, 0xffff0000, v125
	v_pk_add_f32 v[104:105], v[104:105], v[112:113]
	v_pk_add_f32 v[108:109], v[108:109], v[110:111]
	s_waitcnt vmcnt(3)
	v_lshlrev_b32_e32 v110, 16, v126
	v_and_b32_e32 v111, 0xffff0000, v126
	v_lshlrev_b32_e32 v112, 16, v127
	v_and_b32_e32 v113, 0xffff0000, v127
	v_pk_add_f32 v[106:107], v[106:107], v[110:111]
	v_pk_add_f32 v[102:103], v[102:103], v[112:113]
	v_lshlrev_b32_e32 v110, 16, v128
	v_and_b32_e32 v111, 0xffff0000, v128
	v_lshlrev_b32_e32 v112, 16, v129
	v_and_b32_e32 v113, 0xffff0000, v129
	v_pk_add_f32 v[108:109], v[108:109], v[110:111]
	v_pk_add_f32 v[104:105], v[104:105], v[112:113]
	s_waitcnt vmcnt(1)
	v_lshlrev_b32_e32 v110, 16, v156
	v_and_b32_e32 v111, 0xffff0000, v156
	v_lshlrev_b32_e32 v112, 16, v157
	v_and_b32_e32 v113, 0xffff0000, v157
	v_pk_add_f32 v[102:103], v[102:103], v[112:113]
	v_pk_add_f32 v[106:107], v[106:107], v[110:111]
	v_lshlrev_b32_e32 v110, 16, v158
	v_and_b32_e32 v111, 0xffff0000, v158
	v_lshlrev_b32_e32 v112, 16, v159
	v_and_b32_e32 v113, 0xffff0000, v159
	v_pk_add_f32 v[112:113], v[104:105], v[112:113]
	v_pk_add_f32 v[108:109], v[108:109], v[110:111]
	v_cvt_pk_bf16_f32 v105, v102, v103
	v_lshlrev_b64 v[102:103], 12, v[160:161]
	v_cvt_pk_bf16_f32 v104, v106, v107
	v_cvt_pk_bf16_f32 v106, v108, v109
	v_lshl_add_u64 v[108:109], s[40:41], 0, v[102:103]
	v_cvt_pk_bf16_f32 v107, v112, v113
	v_lshl_add_u64 v[108:109], v[146:147], 1, v[108:109]
	global_store_dwordx4 v[108:109], v[104:107], off
	v_lshlrev_b32_e32 v108, 16, v94
	v_and_b32_e32 v109, 0xffff0000, v94
	v_lshlrev_b32_e32 v104, 16, v98
	v_and_b32_e32 v105, 0xffff0000, v98
	v_lshlrev_b32_e32 v98, 16, v99
	v_and_b32_e32 v99, 0xffff0000, v99
	v_pk_add_f32 v[104:105], v[104:105], 0 op_sel_hi:[1,0]
	v_pk_add_f32 v[98:99], v[98:99], 0 op_sel_hi:[1,0]
	v_lshlrev_b32_e32 v106, 16, v100
	v_and_b32_e32 v107, 0xffff0000, v100
	v_lshlrev_b32_e32 v100, 16, v101
	v_and_b32_e32 v101, 0xffff0000, v101
	v_lshlrev_b32_e32 v94, 16, v95
	v_and_b32_e32 v95, 0xffff0000, v95
	v_pk_add_f32 v[106:107], v[106:107], 0 op_sel_hi:[1,0]
	v_pk_add_f32 v[100:101], v[100:101], 0 op_sel_hi:[1,0]
	v_pk_add_f32 v[94:95], v[98:99], v[94:95]
	v_pk_add_f32 v[98:99], v[104:105], v[108:109]
	v_lshlrev_b32_e32 v104, 16, v96
	v_and_b32_e32 v105, 0xffff0000, v96
	v_lshlrev_b32_e32 v96, 16, v97
	v_and_b32_e32 v97, 0xffff0000, v97
	v_pk_add_f32 v[96:97], v[100:101], v[96:97]
	v_pk_add_f32 v[100:101], v[106:107], v[104:105]
	v_lshlrev_b32_e32 v104, 16, v90
	v_and_b32_e32 v105, 0xffff0000, v90
	v_lshlrev_b32_e32 v90, 16, v91
	v_and_b32_e32 v91, 0xffff0000, v91
	v_pk_add_f32 v[90:91], v[94:95], v[90:91]
	v_lshlrev_b32_e32 v94, 16, v92
	v_and_b32_e32 v95, 0xffff0000, v92
	v_lshlrev_b32_e32 v92, 16, v93
	v_and_b32_e32 v93, 0xffff0000, v93
	v_pk_add_f32 v[98:99], v[98:99], v[104:105]
	v_pk_add_f32 v[92:93], v[96:97], v[92:93]
	v_lshlrev_b32_e32 v96, 16, v86
	v_and_b32_e32 v97, 0xffff0000, v86
	v_lshlrev_b32_e32 v86, 16, v87
	v_and_b32_e32 v87, 0xffff0000, v87
	v_pk_add_f32 v[94:95], v[100:101], v[94:95]
	v_pk_add_f32 v[86:87], v[90:91], v[86:87]
	v_pk_add_f32 v[90:91], v[98:99], v[96:97]
	v_lshlrev_b32_e32 v96, 16, v88
	v_and_b32_e32 v97, 0xffff0000, v88
	v_lshlrev_b32_e32 v88, 16, v89
	v_and_b32_e32 v89, 0xffff0000, v89
	v_pk_add_f32 v[88:89], v[92:93], v[88:89]
	v_pk_add_f32 v[92:93], v[94:95], v[96:97]
	v_lshlrev_b32_e32 v94, 16, v82
	v_and_b32_e32 v95, 0xffff0000, v82
	v_lshlrev_b32_e32 v82, 16, v83
	v_and_b32_e32 v83, 0xffff0000, v83
	v_pk_add_f32 v[82:83], v[86:87], v[82:83]
	v_lshlrev_b32_e32 v86, 16, v84
	v_and_b32_e32 v87, 0xffff0000, v84
	v_lshlrev_b32_e32 v84, 16, v85
	v_and_b32_e32 v85, 0xffff0000, v85
	v_pk_add_f32 v[90:91], v[90:91], v[94:95]
	v_pk_add_f32 v[84:85], v[88:89], v[84:85]
	v_lshlrev_b32_e32 v88, 16, v78
	v_and_b32_e32 v89, 0xffff0000, v78
	v_lshlrev_b32_e32 v78, 16, v79
	v_and_b32_e32 v79, 0xffff0000, v79
	v_pk_add_f32 v[86:87], v[92:93], v[86:87]
	v_pk_add_f32 v[78:79], v[82:83], v[78:79]
	v_pk_add_f32 v[82:83], v[90:91], v[88:89]
	v_lshlrev_b32_e32 v88, 16, v80
	v_and_b32_e32 v89, 0xffff0000, v80
	v_lshlrev_b32_e32 v80, 16, v81
	v_and_b32_e32 v81, 0xffff0000, v81
	v_pk_add_f32 v[80:81], v[84:85], v[80:81]
	v_pk_add_f32 v[84:85], v[86:87], v[88:89]
	v_lshlrev_b32_e32 v86, 16, v74
	v_and_b32_e32 v87, 0xffff0000, v74
	v_lshlrev_b32_e32 v74, 16, v75
	v_and_b32_e32 v75, 0xffff0000, v75
	v_pk_add_f32 v[74:75], v[78:79], v[74:75]
	v_lshlrev_b32_e32 v78, 16, v76
	v_and_b32_e32 v79, 0xffff0000, v76
	v_lshlrev_b32_e32 v76, 16, v77
	v_and_b32_e32 v77, 0xffff0000, v77
	v_pk_add_f32 v[78:79], v[84:85], v[78:79]
	s_waitcnt vmcnt(1)
	v_lshlrev_b32_e32 v84, 16, v70
	v_and_b32_e32 v85, 0xffff0000, v70
	v_lshlrev_b32_e32 v70, 16, v71
	v_and_b32_e32 v71, 0xffff0000, v71
	v_pk_add_f32 v[82:83], v[82:83], v[86:87]
	v_pk_add_f32 v[80:81], v[80:81], v[76:77]
	v_pk_add_f32 v[76:77], v[74:75], v[70:71]
	v_lshlrev_b32_e32 v70, 16, v72
	v_and_b32_e32 v71, 0xffff0000, v72
	v_lshlrev_b32_e32 v72, 16, v73
	v_and_b32_e32 v73, 0xffff0000, v73
	v_pk_add_f32 v[74:75], v[82:83], v[84:85]
	v_pk_add_f32 v[72:73], v[80:81], v[72:73]
	v_pk_add_f32 v[70:71], v[78:79], v[70:71]

.LBB0_709:
	s_or_b64 exec, exec, s[52:53]
	buffer_inv sc1
	s_mov_b32 s8, 0x400001
	s_branch .LBB0_711

.LBB0_711:
	global_load_dword v70, v133, s[36:37] sc1
	s_mov_b64 s[46:47], -1
	s_waitcnt vmcnt(0)
	v_cmp_lt_u32_e32 vcc, 7, v70
	s_cbranch_vccnz .LBB0_710
	s_sleep 2
	global_load_dword v70, v133, s[36:37] sc1
	s_waitcnt vmcnt(0)
	v_cmp_gt_u32_e32 vcc, 8, v70
	s_cbranch_vccz .LBB0_710
	s_sleep 2
	global_load_dword v70, v133, s[36:37] sc1
	s_waitcnt vmcnt(0)
	v_cmp_gt_u32_e32 vcc, 8, v70
	s_cbranch_vccz .LBB0_710
	s_sleep 2
	global_load_dword v70, v133, s[36:37] sc1
	s_waitcnt vmcnt(0)
	v_cmp_gt_u32_e32 vcc, 8, v70
	s_cbranch_vccz .LBB0_710
	s_sleep 2
	global_load_dword v70, v133, s[36:37] sc1
	s_waitcnt vmcnt(0)
	v_cmp_gt_u32_e32 vcc, 8, v70
	s_cbranch_vccz .LBB0_710
	s_add_i32 s8, s8, -5
	s_cmp_eq_u32 s8, 0
	s_cselect_b64 s[46:47], -1, 0
	s_sleep 2
	s_branch .LBB0_710
.LBB0_717:
	s_waitcnt vmcnt(0)
.LBB0_718:
	s_or_b64 exec, exec, s[34:35]
	s_ashr_i32 s31, s30, 31
	s_lshl_b64 s[30:31], s[30:31], 17
	s_lshl_b32 s8, s77, 1
	v_lshl_add_u64 v[70:71], v[138:139], 0, s[30:31]
	s_lshl_b64 s[30:31], s[8:9], 13
	v_lshl_add_u64 v[70:71], v[70:71], 0, s[30:31]
	v_add_co_u32_e32 v72, vcc, 0x2000, v70
	s_nop 1
	v_addc_co_u32_e32 v73, vcc, 0, v71, vcc
	s_barrier
	global_load_dwordx4 v[102:105], v[70:71], off
	global_load_dwordx4 v[98:101], v[72:73], off
	v_add_co_u32_e32 v72, vcc, 0x20000, v70
	s_lshl_b32 s8, s77, 5
	s_nop 0
	v_addc_co_u32_e32 v73, vcc, 0, v71, vcc
	v_add_co_u32_e32 v74, vcc, 0x22000, v70
	s_and_b32 s8, s8, 0x7fffff80
	s_nop 0
	v_addc_co_u32_e32 v75, vcc, 0, v71, vcc
	global_load_dwordx4 v[106:109], v[72:73], off
	global_load_dwordx4 v[94:97], v[74:75], off
	v_add_co_u32_e32 v72, vcc, 0x40000, v70
	v_add_u32_e32 v147, s8, v148
	s_nop 0
	v_addc_co_u32_e32 v73, vcc, 0, v71, vcc
	v_add_co_u32_e32 v74, vcc, 0x42000, v70
	s_lshl_b32 s8, s77, 4
	s_nop 0
	v_addc_co_u32_e32 v75, vcc, 0, v71, vcc
	global_load_dwordx4 v[110:113], v[72:73], off
	global_load_dwordx4 v[90:93], v[74:75], off
	v_add_co_u32_e32 v72, vcc, 0x60000, v70
	v_and_or_b32 v160, s8, 48, v147
	s_nop 0
	v_addc_co_u32_e32 v73, vcc, 0, v71, vcc
	v_add_co_u32_e32 v74, vcc, 0x62000, v70
	v_ashrrev_i32_e32 v161, 31, v160
	s_nop 0
	v_addc_co_u32_e32 v75, vcc, 0, v71, vcc
	global_load_dwordx4 v[114:117], v[72:73], off
	global_load_dwordx4 v[86:89], v[74:75], off
	v_add_co_u32_e32 v72, vcc, 0x80000, v70
	v_ashrrev_i32_e32 v147, 31, v146
	s_nop 0
	v_addc_co_u32_e32 v73, vcc, 0, v71, vcc
	v_add_co_u32_e32 v74, vcc, 0x82000, v70
	s_mov_b64 s[30:31], 0
	s_nop 0
	v_addc_co_u32_e32 v75, vcc, 0, v71, vcc
	global_load_dwordx4 v[118:121], v[72:73], off
	global_load_dwordx4 v[82:85], v[74:75], off
	v_add_co_u32_e32 v72, vcc, 0xa0000, v70
	s_waitcnt vmcnt(9)
	v_lshlrev_b32_e32 v162, 16, v102
	v_addc_co_u32_e32 v73, vcc, 0, v71, vcc
	v_add_co_u32_e32 v74, vcc, 0xa2000, v70
	v_and_b32_e32 v163, 0xffff0000, v102
	s_nop 0
	v_addc_co_u32_e32 v75, vcc, 0, v71, vcc
	global_load_dwordx4 v[122:125], v[72:73], off
	global_load_dwordx4 v[78:81], v[74:75], off
	v_add_co_u32_e32 v72, vcc, 0xc0000, v70
	v_lshlrev_b32_e32 v102, 16, v103
	s_nop 0
	v_addc_co_u32_e32 v73, vcc, 0, v71, vcc
	v_add_co_u32_e32 v74, vcc, 0xc2000, v70
	v_and_b32_e32 v103, 0xffff0000, v103
	s_nop 0
	v_addc_co_u32_e32 v75, vcc, 0, v71, vcc
	global_load_dwordx4 v[126:129], v[72:73], off
	s_nop 0
	global_load_dwordx4 v[74:77], v[74:75], off
	v_add_co_u32_e32 v72, vcc, 0xe0000, v70
	v_pk_add_f32 v[162:163], v[162:163], 0 op_sel_hi:[1,0]
	s_nop 0
	v_addc_co_u32_e32 v73, vcc, 0, v71, vcc
	v_add_co_u32_e32 v70, vcc, 0xe2000, v70
	v_pk_add_f32 v[102:103], v[102:103], 0 op_sel_hi:[1,0]
	s_nop 0
	v_addc_co_u32_e32 v71, vcc, 0, v71, vcc
	global_load_dwordx4 v[156:159], v[72:73], off
	s_nop 0
	global_load_dwordx4 v[70:73], v[70:71], off
	v_lshlrev_b32_e32 v164, 16, v104
	v_and_b32_e32 v165, 0xffff0000, v104
	v_lshlrev_b32_e32 v104, 16, v105
	v_and_b32_e32 v105, 0xffff0000, v105
	s_waitcnt vmcnt(13)
	v_lshlrev_b32_e32 v166, 16, v106
	v_and_b32_e32 v167, 0xffff0000, v106
	v_lshlrev_b32_e32 v106, 16, v107
	v_and_b32_e32 v107, 0xffff0000, v107
	v_pk_add_f32 v[164:165], v[164:165], 0 op_sel_hi:[1,0]
	v_pk_add_f32 v[104:105], v[104:105], 0 op_sel_hi:[1,0]
	v_pk_add_f32 v[102:103], v[102:103], v[106:107]
	v_pk_add_f32 v[106:107], v[162:163], v[166:167]
	v_lshlrev_b32_e32 v162, 16, v108
	v_and_b32_e32 v163, 0xffff0000, v108
	v_lshlrev_b32_e32 v108, 16, v109
	v_and_b32_e32 v109, 0xffff0000, v109
	v_pk_add_f32 v[104:105], v[104:105], v[108:109]
	v_pk_add_f32 v[108:109], v[164:165], v[162:163]
	s_waitcnt vmcnt(11)
	v_lshlrev_b32_e32 v162, 16, v110
	v_and_b32_e32 v163, 0xffff0000, v110
	v_lshlrev_b32_e32 v110, 16, v111
	v_and_b32_e32 v111, 0xffff0000, v111
	v_pk_add_f32 v[102:103], v[102:103], v[110:111]
	v_lshlrev_b32_e32 v110, 16, v112
	v_and_b32_e32 v111, 0xffff0000, v112
	v_lshlrev_b32_e32 v112, 16, v113
	v_and_b32_e32 v113, 0xffff0000, v113
	v_pk_add_f32 v[106:107], v[106:107], v[162:163]
	v_pk_add_f32 v[108:109], v[108:109], v[110:111]
	v_pk_add_f32 v[104:105], v[104:105], v[112:113]
	s_waitcnt vmcnt(9)
	v_lshlrev_b32_e32 v110, 16, v114
	v_and_b32_e32 v111, 0xffff0000, v114
	v_lshlrev_b32_e32 v112, 16, v115
	v_and_b32_e32 v113, 0xffff0000, v115
	v_pk_add_f32 v[102:103], v[102:103], v[112:113]
	v_pk_add_f32 v[106:107], v[106:107], v[110:111]
	v_lshlrev_b32_e32 v110, 16, v116
	v_and_b32_e32 v111, 0xffff0000, v116
	v_lshlrev_b32_e32 v112, 16, v117
	v_and_b32_e32 v113, 0xffff0000, v117
	v_pk_add_f32 v[104:105], v[104:105], v[112:113]
	v_pk_add_f32 v[108:109], v[108:109], v[110:111]
	s_waitcnt vmcnt(7)
	v_lshlrev_b32_e32 v110, 16, v118
	v_and_b32_e32 v111, 0xffff0000, v118
	v_lshlrev_b32_e32 v112, 16, v119
	v_and_b32_e32 v113, 0xffff0000, v119
	v_pk_add_f32 v[106:107], v[106:107], v[110:111]
	v_pk_add_f32 v[102:103], v[102:103], v[112:113]
	v_lshlrev_b32_e32 v110, 16, v120
	v_and_b32_e32 v111, 0xffff0000, v120
	v_lshlrev_b32_e32 v112, 16, v121
	v_and_b32_e32 v113, 0xffff0000, v121
	v_pk_add_f32 v[108:109], v[108:109], v[110:111]
	v_pk_add_f32 v[104:105], v[104:105], v[112:113]
	s_waitcnt vmcnt(5)
	v_lshlrev_b32_e32 v110, 16, v122
	v_and_b32_e32 v111, 0xffff0000, v122
	v_lshlrev_b32_e32 v112, 16, v123
	v_and_b32_e32 v113, 0xffff0000, v123
	v_pk_add_f32 v[102:103], v[102:103], v[112:113]
	v_pk_add_f32 v[106:107], v[106:107], v[110:111]
	v_lshlrev_b32_e32 v110, 16, v124
	v_and_b32_e32 v111, 0xffff0000, v124
	v_lshlrev_b32_e32 v112, 16, v125
	v_and_b32_e32 v113, 0xffff0000, v125
	v_pk_add_f32 v[104:105], v[104:105], v[112:113]
	v_pk_add_f32 v[108:109], v[108:109], v[110:111]
	s_waitcnt vmcnt(3)
	v_lshlrev_b32_e32 v110, 16, v126
	v_and_b32_e32 v111, 0xffff0000, v126
	v_lshlrev_b32_e32 v112, 16, v127
	v_and_b32_e32 v113, 0xffff0000, v127
	v_pk_add_f32 v[106:107], v[106:107], v[110:111]
	v_pk_add_f32 v[102:103], v[102:103], v[112:113]
	v_lshlrev_b32_e32 v110, 16, v128
	v_and_b32_e32 v111, 0xffff0000, v128
	v_lshlrev_b32_e32 v112, 16, v129
	v_and_b32_e32 v113, 0xffff0000, v129
	v_pk_add_f32 v[108:109], v[108:109], v[110:111]
	v_pk_add_f32 v[104:105], v[104:105], v[112:113]
	s_waitcnt vmcnt(1)
	v_lshlrev_b32_e32 v110, 16, v156
	v_and_b32_e32 v111, 0xffff0000, v156
	v_lshlrev_b32_e32 v112, 16, v157
	v_and_b32_e32 v113, 0xffff0000, v157
	v_pk_add_f32 v[102:103], v[102:103], v[112:113]
	v_pk_add_f32 v[106:107], v[106:107], v[110:111]
	v_lshlrev_b32_e32 v110, 16, v158
	v_and_b32_e32 v111, 0xffff0000, v158
	v_lshlrev_b32_e32 v112, 16, v159
	v_and_b32_e32 v113, 0xffff0000, v159
	v_pk_add_f32 v[112:113], v[104:105], v[112:113]
	v_pk_add_f32 v[108:109], v[108:109], v[110:111]
	v_cvt_pk_bf16_f32 v105, v102, v103
	v_lshlrev_b64 v[102:103], 12, v[160:161]
	v_cvt_pk_bf16_f32 v104, v106, v107
	v_cvt_pk_bf16_f32 v106, v108, v109
	v_lshl_add_u64 v[108:109], s[40:41], 0, v[102:103]
	v_cvt_pk_bf16_f32 v107, v112, v113
	v_lshl_add_u64 v[108:109], v[146:147], 1, v[108:109]
	global_store_dwordx4 v[108:109], v[104:107], off
	v_lshlrev_b32_e32 v108, 16, v94
	v_and_b32_e32 v109, 0xffff0000, v94
	v_lshlrev_b32_e32 v104, 16, v98
	v_and_b32_e32 v105, 0xffff0000, v98
	v_lshlrev_b32_e32 v98, 16, v99
	v_and_b32_e32 v99, 0xffff0000, v99
	v_pk_add_f32 v[104:105], v[104:105], 0 op_sel_hi:[1,0]
	v_pk_add_f32 v[98:99], v[98:99], 0 op_sel_hi:[1,0]
	v_lshlrev_b32_e32 v106, 16, v100
	v_and_b32_e32 v107, 0xffff0000, v100
	v_lshlrev_b32_e32 v100, 16, v101
	v_and_b32_e32 v101, 0xffff0000, v101
	v_lshlrev_b32_e32 v94, 16, v95
	v_and_b32_e32 v95, 0xffff0000, v95
	v_pk_add_f32 v[106:107], v[106:107], 0 op_sel_hi:[1,0]
	v_pk_add_f32 v[100:101], v[100:101], 0 op_sel_hi:[1,0]
	v_pk_add_f32 v[94:95], v[98:99], v[94:95]
	v_pk_add_f32 v[98:99], v[104:105], v[108:109]
	v_lshlrev_b32_e32 v104, 16, v96
	v_and_b32_e32 v105, 0xffff0000, v96
	v_lshlrev_b32_e32 v96, 16, v97
	v_and_b32_e32 v97, 0xffff0000, v97
	v_pk_add_f32 v[96:97], v[100:101], v[96:97]
	v_pk_add_f32 v[100:101], v[106:107], v[104:105]
	v_lshlrev_b32_e32 v104, 16, v90
	v_and_b32_e32 v105, 0xffff0000, v90
	v_lshlrev_b32_e32 v90, 16, v91
	v_and_b32_e32 v91, 0xffff0000, v91
	v_pk_add_f32 v[90:91], v[94:95], v[90:91]
	v_lshlrev_b32_e32 v94, 16, v92
	v_and_b32_e32 v95, 0xffff0000, v92
	v_lshlrev_b32_e32 v92, 16, v93
	v_and_b32_e32 v93, 0xffff0000, v93
	v_pk_add_f32 v[98:99], v[98:99], v[104:105]
	v_pk_add_f32 v[92:93], v[96:97], v[92:93]
	v_lshlrev_b32_e32 v96, 16, v86
	v_and_b32_e32 v97, 0xffff0000, v86
	v_lshlrev_b32_e32 v86, 16, v87
	v_and_b32_e32 v87, 0xffff0000, v87
	v_pk_add_f32 v[94:95], v[100:101], v[94:95]
	v_pk_add_f32 v[86:87], v[90:91], v[86:87]
	v_pk_add_f32 v[90:91], v[98:99], v[96:97]
	v_lshlrev_b32_e32 v96, 16, v88
	v_and_b32_e32 v97, 0xffff0000, v88
	v_lshlrev_b32_e32 v88, 16, v89
	v_and_b32_e32 v89, 0xffff0000, v89
	v_pk_add_f32 v[88:89], v[92:93], v[88:89]
	v_pk_add_f32 v[92:93], v[94:95], v[96:97]
	v_lshlrev_b32_e32 v94, 16, v82
	v_and_b32_e32 v95, 0xffff0000, v82
	v_lshlrev_b32_e32 v82, 16, v83
	v_and_b32_e32 v83, 0xffff0000, v83
	v_pk_add_f32 v[82:83], v[86:87], v[82:83]
	v_lshlrev_b32_e32 v86, 16, v84
	v_and_b32_e32 v87, 0xffff0000, v84
	v_lshlrev_b32_e32 v84, 16, v85
	v_and_b32_e32 v85, 0xffff0000, v85
	v_pk_add_f32 v[90:91], v[90:91], v[94:95]
	v_pk_add_f32 v[84:85], v[88:89], v[84:85]
	v_lshlrev_b32_e32 v88, 16, v78
	v_and_b32_e32 v89, 0xffff0000, v78
	v_lshlrev_b32_e32 v78, 16, v79
	v_and_b32_e32 v79, 0xffff0000, v79
	v_pk_add_f32 v[86:87], v[92:93], v[86:87]
	v_pk_add_f32 v[78:79], v[82:83], v[78:79]
	v_pk_add_f32 v[82:83], v[90:91], v[88:89]
	v_lshlrev_b32_e32 v88, 16, v80
	v_and_b32_e32 v89, 0xffff0000, v80
	v_lshlrev_b32_e32 v80, 16, v81
	v_and_b32_e32 v81, 0xffff0000, v81
	v_pk_add_f32 v[80:81], v[84:85], v[80:81]
	v_pk_add_f32 v[84:85], v[86:87], v[88:89]
	v_lshlrev_b32_e32 v86, 16, v74
	v_and_b32_e32 v87, 0xffff0000, v74
	v_lshlrev_b32_e32 v74, 16, v75
	v_and_b32_e32 v75, 0xffff0000, v75
	v_pk_add_f32 v[74:75], v[78:79], v[74:75]
	v_lshlrev_b32_e32 v78, 16, v76
	v_and_b32_e32 v79, 0xffff0000, v76
	v_lshlrev_b32_e32 v76, 16, v77
	v_and_b32_e32 v77, 0xffff0000, v77
	v_pk_add_f32 v[78:79], v[84:85], v[78:79]
	s_waitcnt vmcnt(1)
	v_lshlrev_b32_e32 v84, 16, v70
	v_and_b32_e32 v85, 0xffff0000, v70
	v_lshlrev_b32_e32 v70, 16, v71
	v_and_b32_e32 v71, 0xffff0000, v71
	v_pk_add_f32 v[82:83], v[82:83], v[86:87]
	v_pk_add_f32 v[80:81], v[80:81], v[76:77]
	v_pk_add_f32 v[76:77], v[74:75], v[70:71]
	v_lshlrev_b32_e32 v70, 16, v72
	v_and_b32_e32 v71, 0xffff0000, v72
	v_lshlrev_b32_e32 v72, 16, v73
	v_and_b32_e32 v73, 0xffff0000, v73
	v_pk_add_f32 v[74:75], v[82:83], v[84:85]
	v_pk_add_f32 v[72:73], v[80:81], v[72:73]
	v_pk_add_f32 v[70:71], v[78:79], v[70:71]

.LBB0_1266:
	s_or_b64 exec, exec, s[56:57]
	buffer_inv sc1
	s_mov_b32 s8, 0x400001
	s_branch .LBB0_1268

.LBB0_1268:
	global_load_dword v70, v133, s[50:51] sc1
	s_mov_b64 s[54:55], -1
	s_waitcnt vmcnt(0)
	v_cmp_lt_u32_e32 vcc, 7, v70
	s_cbranch_vccnz .LBB0_1267
	s_sleep 2
	global_load_dword v70, v133, s[50:51] sc1
	s_waitcnt vmcnt(0)
	v_cmp_gt_u32_e32 vcc, 8, v70
	s_cbranch_vccz .LBB0_1267
	s_sleep 2
	global_load_dword v70, v133, s[50:51] sc1
	s_waitcnt vmcnt(0)
	v_cmp_gt_u32_e32 vcc, 8, v70
	s_cbranch_vccz .LBB0_1267
	s_sleep 2
	global_load_dword v70, v133, s[50:51] sc1
	s_waitcnt vmcnt(0)
	v_cmp_gt_u32_e32 vcc, 8, v70
	s_cbranch_vccz .LBB0_1267
	s_sleep 2
	global_load_dword v70, v133, s[50:51] sc1
	s_waitcnt vmcnt(0)
	v_cmp_gt_u32_e32 vcc, 8, v70
	s_cbranch_vccz .LBB0_1267
	s_add_i32 s8, s8, -5
	s_cmp_eq_u32 s8, 0
	s_cselect_b64 s[54:55], -1, 0
	s_sleep 2
	s_branch .LBB0_1267
.LBB0_1274:
	s_waitcnt vmcnt(0)
.LBB0_1275:
	s_or_b64 exec, exec, s[48:49]
	s_ashr_i32 s37, s36, 31
	s_lshl_b64 s[36:37], s[36:37], 17
	s_lshl_b32 s8, s81, 1
	v_lshl_add_u64 v[70:71], v[138:139], 0, s[36:37]
	s_lshl_b64 s[36:37], s[8:9], 13
	v_lshl_add_u64 v[70:71], v[70:71], 0, s[36:37]
	v_add_co_u32_e32 v72, vcc, 0x2000, v70
	s_nop 1
	v_addc_co_u32_e32 v73, vcc, 0, v71, vcc
	s_barrier
	global_load_dwordx4 v[102:105], v[70:71], off
	global_load_dwordx4 v[98:101], v[72:73], off
	v_add_co_u32_e32 v72, vcc, 0x20000, v70
	s_lshl_b32 s8, s81, 5
	s_nop 0
	v_addc_co_u32_e32 v73, vcc, 0, v71, vcc
	v_add_co_u32_e32 v74, vcc, 0x22000, v70
	s_and_b32 s8, s8, 0x7fffff80
	s_nop 0
	v_addc_co_u32_e32 v75, vcc, 0, v71, vcc
	global_load_dwordx4 v[106:109], v[72:73], off
	global_load_dwordx4 v[94:97], v[74:75], off
	v_add_co_u32_e32 v72, vcc, 0x40000, v70
	v_add_u32_e32 v147, s8, v148
	s_nop 0
	v_addc_co_u32_e32 v73, vcc, 0, v71, vcc
	v_add_co_u32_e32 v74, vcc, 0x42000, v70
	s_lshl_b32 s8, s81, 4
	s_nop 0
	v_addc_co_u32_e32 v75, vcc, 0, v71, vcc
	global_load_dwordx4 v[110:113], v[72:73], off
	global_load_dwordx4 v[90:93], v[74:75], off
	v_add_co_u32_e32 v72, vcc, 0x60000, v70
	v_and_or_b32 v160, s8, 48, v147
	s_nop 0
	v_addc_co_u32_e32 v73, vcc, 0, v71, vcc
	v_add_co_u32_e32 v74, vcc, 0x62000, v70
	v_ashrrev_i32_e32 v161, 31, v160
	s_nop 0
	v_addc_co_u32_e32 v75, vcc, 0, v71, vcc
	global_load_dwordx4 v[114:117], v[72:73], off
	global_load_dwordx4 v[86:89], v[74:75], off
	v_add_co_u32_e32 v72, vcc, 0x80000, v70
	v_ashrrev_i32_e32 v147, 31, v146
	s_nop 0
	v_addc_co_u32_e32 v73, vcc, 0, v71, vcc
	v_add_co_u32_e32 v74, vcc, 0x82000, v70
	s_mov_b64 s[36:37], 0
	s_nop 0
	v_addc_co_u32_e32 v75, vcc, 0, v71, vcc
	global_load_dwordx4 v[118:121], v[72:73], off
	global_load_dwordx4 v[82:85], v[74:75], off
	v_add_co_u32_e32 v72, vcc, 0xa0000, v70
	s_waitcnt vmcnt(9)
	v_lshlrev_b32_e32 v162, 16, v102
	v_addc_co_u32_e32 v73, vcc, 0, v71, vcc
	v_add_co_u32_e32 v74, vcc, 0xa2000, v70
	v_and_b32_e32 v163, 0xffff0000, v102
	s_nop 0
	v_addc_co_u32_e32 v75, vcc, 0, v71, vcc
	global_load_dwordx4 v[122:125], v[72:73], off
	global_load_dwordx4 v[78:81], v[74:75], off
	v_add_co_u32_e32 v72, vcc, 0xc0000, v70
	v_lshlrev_b32_e32 v102, 16, v103
	s_nop 0
	v_addc_co_u32_e32 v73, vcc, 0, v71, vcc
	v_add_co_u32_e32 v74, vcc, 0xc2000, v70
	v_and_b32_e32 v103, 0xffff0000, v103
	s_nop 0
	v_addc_co_u32_e32 v75, vcc, 0, v71, vcc
	global_load_dwordx4 v[126:129], v[72:73], off
	s_nop 0
	global_load_dwordx4 v[74:77], v[74:75], off
	v_add_co_u32_e32 v72, vcc, 0xe0000, v70
	v_pk_add_f32 v[162:163], v[162:163], 0 op_sel_hi:[1,0]
	s_nop 0
	v_addc_co_u32_e32 v73, vcc, 0, v71, vcc
	v_add_co_u32_e32 v70, vcc, 0xe2000, v70
	v_pk_add_f32 v[102:103], v[102:103], 0 op_sel_hi:[1,0]
	s_nop 0
	v_addc_co_u32_e32 v71, vcc, 0, v71, vcc
	global_load_dwordx4 v[156:159], v[72:73], off
	s_nop 0
	global_load_dwordx4 v[70:73], v[70:71], off
	v_lshlrev_b32_e32 v164, 16, v104
	v_and_b32_e32 v165, 0xffff0000, v104
	v_lshlrev_b32_e32 v104, 16, v105
	v_and_b32_e32 v105, 0xffff0000, v105
	s_waitcnt vmcnt(13)
	v_lshlrev_b32_e32 v166, 16, v106
	v_and_b32_e32 v167, 0xffff0000, v106
	v_lshlrev_b32_e32 v106, 16, v107
	v_and_b32_e32 v107, 0xffff0000, v107
	v_pk_add_f32 v[164:165], v[164:165], 0 op_sel_hi:[1,0]
	v_pk_add_f32 v[104:105], v[104:105], 0 op_sel_hi:[1,0]
	v_pk_add_f32 v[102:103], v[102:103], v[106:107]
	v_pk_add_f32 v[106:107], v[162:163], v[166:167]
	v_lshlrev_b32_e32 v162, 16, v108
	v_and_b32_e32 v163, 0xffff0000, v108
	v_lshlrev_b32_e32 v108, 16, v109
	v_and_b32_e32 v109, 0xffff0000, v109
	v_pk_add_f32 v[104:105], v[104:105], v[108:109]
	v_pk_add_f32 v[108:109], v[164:165], v[162:163]
	s_waitcnt vmcnt(11)
	v_lshlrev_b32_e32 v162, 16, v110
	v_and_b32_e32 v163, 0xffff0000, v110
	v_lshlrev_b32_e32 v110, 16, v111
	v_and_b32_e32 v111, 0xffff0000, v111
	v_pk_add_f32 v[102:103], v[102:103], v[110:111]
	v_lshlrev_b32_e32 v110, 16, v112
	v_and_b32_e32 v111, 0xffff0000, v112
	v_lshlrev_b32_e32 v112, 16, v113
	v_and_b32_e32 v113, 0xffff0000, v113
	v_pk_add_f32 v[106:107], v[106:107], v[162:163]
	v_pk_add_f32 v[108:109], v[108:109], v[110:111]
	v_pk_add_f32 v[104:105], v[104:105], v[112:113]
	s_waitcnt vmcnt(9)
	v_lshlrev_b32_e32 v110, 16, v114
	v_and_b32_e32 v111, 0xffff0000, v114
	v_lshlrev_b32_e32 v112, 16, v115
	v_and_b32_e32 v113, 0xffff0000, v115
	v_pk_add_f32 v[102:103], v[102:103], v[112:113]
	v_pk_add_f32 v[106:107], v[106:107], v[110:111]
	v_lshlrev_b32_e32 v110, 16, v116
	v_and_b32_e32 v111, 0xffff0000, v116
	v_lshlrev_b32_e32 v112, 16, v117
	v_and_b32_e32 v113, 0xffff0000, v117
	v_pk_add_f32 v[104:105], v[104:105], v[112:113]
	v_pk_add_f32 v[108:109], v[108:109], v[110:111]
	s_waitcnt vmcnt(7)
	v_lshlrev_b32_e32 v110, 16, v118
	v_and_b32_e32 v111, 0xffff0000, v118
	v_lshlrev_b32_e32 v112, 16, v119
	v_and_b32_e32 v113, 0xffff0000, v119
	v_pk_add_f32 v[106:107], v[106:107], v[110:111]
	v_pk_add_f32 v[102:103], v[102:103], v[112:113]
	v_lshlrev_b32_e32 v110, 16, v120
	v_and_b32_e32 v111, 0xffff0000, v120
	v_lshlrev_b32_e32 v112, 16, v121
	v_and_b32_e32 v113, 0xffff0000, v121
	v_pk_add_f32 v[108:109], v[108:109], v[110:111]
	v_pk_add_f32 v[104:105], v[104:105], v[112:113]
	s_waitcnt vmcnt(5)
	v_lshlrev_b32_e32 v110, 16, v122
	v_and_b32_e32 v111, 0xffff0000, v122
	v_lshlrev_b32_e32 v112, 16, v123
	v_and_b32_e32 v113, 0xffff0000, v123
	v_pk_add_f32 v[102:103], v[102:103], v[112:113]
	v_pk_add_f32 v[106:107], v[106:107], v[110:111]
	v_lshlrev_b32_e32 v110, 16, v124
	v_and_b32_e32 v111, 0xffff0000, v124
	v_lshlrev_b32_e32 v112, 16, v125
	v_and_b32_e32 v113, 0xffff0000, v125
	v_pk_add_f32 v[104:105], v[104:105], v[112:113]
	v_pk_add_f32 v[108:109], v[108:109], v[110:111]
	s_waitcnt vmcnt(3)
	v_lshlrev_b32_e32 v110, 16, v126
	v_and_b32_e32 v111, 0xffff0000, v126
	v_lshlrev_b32_e32 v112, 16, v127
	v_and_b32_e32 v113, 0xffff0000, v127
	v_pk_add_f32 v[106:107], v[106:107], v[110:111]
	v_pk_add_f32 v[102:103], v[102:103], v[112:113]
	v_lshlrev_b32_e32 v110, 16, v128
	v_and_b32_e32 v111, 0xffff0000, v128
	v_lshlrev_b32_e32 v112, 16, v129
	v_and_b32_e32 v113, 0xffff0000, v129
	v_pk_add_f32 v[108:109], v[108:109], v[110:111]
	v_pk_add_f32 v[104:105], v[104:105], v[112:113]
	s_waitcnt vmcnt(1)
	v_lshlrev_b32_e32 v110, 16, v156
	v_and_b32_e32 v111, 0xffff0000, v156
	v_lshlrev_b32_e32 v112, 16, v157
	v_and_b32_e32 v113, 0xffff0000, v157
	v_pk_add_f32 v[102:103], v[102:103], v[112:113]
	v_pk_add_f32 v[106:107], v[106:107], v[110:111]
	v_lshlrev_b32_e32 v110, 16, v158
	v_and_b32_e32 v111, 0xffff0000, v158
	v_lshlrev_b32_e32 v112, 16, v159
	v_and_b32_e32 v113, 0xffff0000, v159
	v_pk_add_f32 v[112:113], v[104:105], v[112:113]
	v_pk_add_f32 v[108:109], v[108:109], v[110:111]
	v_cvt_pk_bf16_f32 v105, v102, v103
	v_lshlrev_b64 v[102:103], 12, v[160:161]
	v_cvt_pk_bf16_f32 v104, v106, v107
	v_cvt_pk_bf16_f32 v106, v108, v109
	v_lshl_add_u64 v[108:109], s[40:41], 0, v[102:103]
	v_cvt_pk_bf16_f32 v107, v112, v113
	v_lshl_add_u64 v[108:109], v[146:147], 1, v[108:109]
	global_store_dwordx4 v[108:109], v[104:107], off
	v_lshlrev_b32_e32 v108, 16, v94
	v_and_b32_e32 v109, 0xffff0000, v94
	v_lshlrev_b32_e32 v104, 16, v98
	v_and_b32_e32 v105, 0xffff0000, v98
	v_lshlrev_b32_e32 v98, 16, v99
	v_and_b32_e32 v99, 0xffff0000, v99
	v_pk_add_f32 v[104:105], v[104:105], 0 op_sel_hi:[1,0]
	v_pk_add_f32 v[98:99], v[98:99], 0 op_sel_hi:[1,0]
	v_lshlrev_b32_e32 v106, 16, v100
	v_and_b32_e32 v107, 0xffff0000, v100
	v_lshlrev_b32_e32 v100, 16, v101
	v_and_b32_e32 v101, 0xffff0000, v101
	v_lshlrev_b32_e32 v94, 16, v95
	v_and_b32_e32 v95, 0xffff0000, v95
	v_pk_add_f32 v[106:107], v[106:107], 0 op_sel_hi:[1,0]
	v_pk_add_f32 v[100:101], v[100:101], 0 op_sel_hi:[1,0]
	v_pk_add_f32 v[94:95], v[98:99], v[94:95]
	v_pk_add_f32 v[98:99], v[104:105], v[108:109]
	v_lshlrev_b32_e32 v104, 16, v96
	v_and_b32_e32 v105, 0xffff0000, v96
	v_lshlrev_b32_e32 v96, 16, v97
	v_and_b32_e32 v97, 0xffff0000, v97
	v_pk_add_f32 v[96:97], v[100:101], v[96:97]
	v_pk_add_f32 v[100:101], v[106:107], v[104:105]
	v_lshlrev_b32_e32 v104, 16, v90
	v_and_b32_e32 v105, 0xffff0000, v90
	v_lshlrev_b32_e32 v90, 16, v91
	v_and_b32_e32 v91, 0xffff0000, v91
	v_pk_add_f32 v[90:91], v[94:95], v[90:91]
	v_lshlrev_b32_e32 v94, 16, v92
	v_and_b32_e32 v95, 0xffff0000, v92
	v_lshlrev_b32_e32 v92, 16, v93
	v_and_b32_e32 v93, 0xffff0000, v93
	v_pk_add_f32 v[98:99], v[98:99], v[104:105]
	v_pk_add_f32 v[92:93], v[96:97], v[92:93]
	v_lshlrev_b32_e32 v96, 16, v86
	v_and_b32_e32 v97, 0xffff0000, v86
	v_lshlrev_b32_e32 v86, 16, v87
	v_and_b32_e32 v87, 0xffff0000, v87
	v_pk_add_f32 v[94:95], v[100:101], v[94:95]
	v_pk_add_f32 v[86:87], v[90:91], v[86:87]
	v_pk_add_f32 v[90:91], v[98:99], v[96:97]
	v_lshlrev_b32_e32 v96, 16, v88
	v_and_b32_e32 v97, 0xffff0000, v88
	v_lshlrev_b32_e32 v88, 16, v89
	v_and_b32_e32 v89, 0xffff0000, v89
	v_pk_add_f32 v[88:89], v[92:93], v[88:89]
	v_pk_add_f32 v[92:93], v[94:95], v[96:97]
	v_lshlrev_b32_e32 v94, 16, v82
	v_and_b32_e32 v95, 0xffff0000, v82
	v_lshlrev_b32_e32 v82, 16, v83
	v_and_b32_e32 v83, 0xffff0000, v83
	v_pk_add_f32 v[82:83], v[86:87], v[82:83]
	v_lshlrev_b32_e32 v86, 16, v84
	v_and_b32_e32 v87, 0xffff0000, v84
	v_lshlrev_b32_e32 v84, 16, v85
	v_and_b32_e32 v85, 0xffff0000, v85
	v_pk_add_f32 v[90:91], v[90:91], v[94:95]
	v_pk_add_f32 v[84:85], v[88:89], v[84:85]
	v_lshlrev_b32_e32 v88, 16, v78
	v_and_b32_e32 v89, 0xffff0000, v78
	v_lshlrev_b32_e32 v78, 16, v79
	v_and_b32_e32 v79, 0xffff0000, v79
	v_pk_add_f32 v[86:87], v[92:93], v[86:87]
	v_pk_add_f32 v[78:79], v[82:83], v[78:79]
	v_pk_add_f32 v[82:83], v[90:91], v[88:89]
	v_lshlrev_b32_e32 v88, 16, v80
	v_and_b32_e32 v89, 0xffff0000, v80
	v_lshlrev_b32_e32 v80, 16, v81
	v_and_b32_e32 v81, 0xffff0000, v81
	v_pk_add_f32 v[80:81], v[84:85], v[80:81]
	v_pk_add_f32 v[84:85], v[86:87], v[88:89]
	v_lshlrev_b32_e32 v86, 16, v74
	v_and_b32_e32 v87, 0xffff0000, v74
	v_lshlrev_b32_e32 v74, 16, v75
	v_and_b32_e32 v75, 0xffff0000, v75
	v_pk_add_f32 v[74:75], v[78:79], v[74:75]
	v_lshlrev_b32_e32 v78, 16, v76
	v_and_b32_e32 v79, 0xffff0000, v76
	v_lshlrev_b32_e32 v76, 16, v77
	v_and_b32_e32 v77, 0xffff0000, v77
	v_pk_add_f32 v[78:79], v[84:85], v[78:79]
	s_waitcnt vmcnt(1)
	v_lshlrev_b32_e32 v84, 16, v70
	v_and_b32_e32 v85, 0xffff0000, v70
	v_lshlrev_b32_e32 v70, 16, v71
	v_and_b32_e32 v71, 0xffff0000, v71
	v_pk_add_f32 v[82:83], v[82:83], v[86:87]
	v_pk_add_f32 v[80:81], v[80:81], v[76:77]
	v_pk_add_f32 v[76:77], v[74:75], v[70:71]
	v_lshlrev_b32_e32 v70, 16, v72
	v_and_b32_e32 v71, 0xffff0000, v72
	v_lshlrev_b32_e32 v72, 16, v73
	v_and_b32_e32 v73, 0xffff0000, v73
	v_pk_add_f32 v[74:75], v[82:83], v[84:85]
	v_pk_add_f32 v[72:73], v[80:81], v[72:73]
	v_pk_add_f32 v[70:71], v[78:79], v[70:71]

.LBB0_1522:
	s_or_b64 exec, exec, s[44:45]
	buffer_inv sc1
	s_mov_b32 s6, 0x400001
	s_branch .LBB0_1524

.LBB0_1524:
	global_load_dword v70, v133, s[36:37] sc1
	s_mov_b64 s[42:43], -1
	s_waitcnt vmcnt(0)
	v_cmp_lt_u32_e32 vcc, 7, v70
	s_cbranch_vccnz .LBB0_1523
	s_sleep 2
	global_load_dword v70, v133, s[36:37] sc1
	s_waitcnt vmcnt(0)
	v_cmp_gt_u32_e32 vcc, 8, v70
	s_cbranch_vccz .LBB0_1523
	s_sleep 2
	global_load_dword v70, v133, s[36:37] sc1
	s_waitcnt vmcnt(0)
	v_cmp_gt_u32_e32 vcc, 8, v70
	s_cbranch_vccz .LBB0_1523
	s_sleep 2
	global_load_dword v70, v133, s[36:37] sc1
	s_waitcnt vmcnt(0)
	v_cmp_gt_u32_e32 vcc, 8, v70
	s_cbranch_vccz .LBB0_1523
	s_sleep 2
	global_load_dword v70, v133, s[36:37] sc1
	s_waitcnt vmcnt(0)
	v_cmp_gt_u32_e32 vcc, 8, v70
	s_cbranch_vccz .LBB0_1523
	s_add_i32 s6, s6, -5
	s_cmp_eq_u32 s6, 0
	s_cselect_b64 s[42:43], -1, 0
	s_sleep 2
	s_branch .LBB0_1523
.LBB0_1530:
	s_waitcnt vmcnt(0)
.LBB0_1531:
	s_or_b64 exec, exec, s[34:35]
	s_ashr_i32 s31, s30, 31
	s_lshl_b64 s[30:31], s[30:31], 17
	s_lshl_b32 s6, s88, 1
	v_lshl_add_u64 v[70:71], v[138:139], 0, s[30:31]
	s_lshl_b64 s[30:31], s[6:7], 13
	v_lshl_add_u64 v[70:71], v[70:71], 0, s[30:31]
	v_add_co_u32_e32 v72, vcc, 0x2000, v70
	s_nop 1
	v_addc_co_u32_e32 v73, vcc, 0, v71, vcc
	s_barrier
	global_load_dwordx4 v[102:105], v[70:71], off
	global_load_dwordx4 v[98:101], v[72:73], off
	v_add_co_u32_e32 v72, vcc, 0x20000, v70
	s_lshl_b32 s6, s88, 5
	s_nop 0
	v_addc_co_u32_e32 v73, vcc, 0, v71, vcc
	v_add_co_u32_e32 v74, vcc, 0x22000, v70
	s_and_b32 s6, s6, 0x7fffff80
	s_nop 0
	v_addc_co_u32_e32 v75, vcc, 0, v71, vcc
	global_load_dwordx4 v[106:109], v[72:73], off
	global_load_dwordx4 v[94:97], v[74:75], off
	v_add_co_u32_e32 v72, vcc, 0x40000, v70
	v_add_u32_e32 v147, s6, v148
	s_nop 0
	v_addc_co_u32_e32 v73, vcc, 0, v71, vcc
	v_add_co_u32_e32 v74, vcc, 0x42000, v70
	s_lshl_b32 s6, s88, 4
	s_nop 0
	v_addc_co_u32_e32 v75, vcc, 0, v71, vcc
	global_load_dwordx4 v[110:113], v[72:73], off
	global_load_dwordx4 v[90:93], v[74:75], off
	v_add_co_u32_e32 v72, vcc, 0x60000, v70
	v_and_or_b32 v160, s6, 48, v147
	s_nop 0
	v_addc_co_u32_e32 v73, vcc, 0, v71, vcc
	v_add_co_u32_e32 v74, vcc, 0x62000, v70
	v_ashrrev_i32_e32 v161, 31, v160
	s_nop 0
	v_addc_co_u32_e32 v75, vcc, 0, v71, vcc
	global_load_dwordx4 v[114:117], v[72:73], off
	global_load_dwordx4 v[86:89], v[74:75], off
	v_add_co_u32_e32 v72, vcc, 0x80000, v70
	v_ashrrev_i32_e32 v147, 31, v146
	s_nop 0
	v_addc_co_u32_e32 v73, vcc, 0, v71, vcc
	v_add_co_u32_e32 v74, vcc, 0x82000, v70
	s_mov_b64 s[30:31], 0
	s_nop 0
	v_addc_co_u32_e32 v75, vcc, 0, v71, vcc
	global_load_dwordx4 v[118:121], v[72:73], off
	global_load_dwordx4 v[82:85], v[74:75], off
	v_add_co_u32_e32 v72, vcc, 0xa0000, v70
	s_waitcnt vmcnt(9)
	v_lshlrev_b32_e32 v162, 16, v102
	v_addc_co_u32_e32 v73, vcc, 0, v71, vcc
	v_add_co_u32_e32 v74, vcc, 0xa2000, v70
	v_and_b32_e32 v163, 0xffff0000, v102
	s_nop 0
	v_addc_co_u32_e32 v75, vcc, 0, v71, vcc
	global_load_dwordx4 v[122:125], v[72:73], off
	global_load_dwordx4 v[78:81], v[74:75], off
	v_add_co_u32_e32 v72, vcc, 0xc0000, v70
	v_lshlrev_b32_e32 v102, 16, v103
	s_nop 0
	v_addc_co_u32_e32 v73, vcc, 0, v71, vcc
	v_add_co_u32_e32 v74, vcc, 0xc2000, v70
	v_and_b32_e32 v103, 0xffff0000, v103
	s_nop 0
	v_addc_co_u32_e32 v75, vcc, 0, v71, vcc
	global_load_dwordx4 v[126:129], v[72:73], off
	s_nop 0
	global_load_dwordx4 v[74:77], v[74:75], off
	v_add_co_u32_e32 v72, vcc, 0xe0000, v70
	v_pk_add_f32 v[162:163], v[162:163], 0 op_sel_hi:[1,0]
	s_nop 0
	v_addc_co_u32_e32 v73, vcc, 0, v71, vcc
	v_add_co_u32_e32 v70, vcc, 0xe2000, v70
	v_pk_add_f32 v[102:103], v[102:103], 0 op_sel_hi:[1,0]
	s_nop 0
	v_addc_co_u32_e32 v71, vcc, 0, v71, vcc
	global_load_dwordx4 v[156:159], v[72:73], off
	s_nop 0
	global_load_dwordx4 v[70:73], v[70:71], off
	v_lshlrev_b32_e32 v164, 16, v104
	v_and_b32_e32 v165, 0xffff0000, v104
	v_lshlrev_b32_e32 v104, 16, v105
	v_and_b32_e32 v105, 0xffff0000, v105
	s_waitcnt vmcnt(13)
	v_lshlrev_b32_e32 v166, 16, v106
	v_and_b32_e32 v167, 0xffff0000, v106
	v_lshlrev_b32_e32 v106, 16, v107
	v_and_b32_e32 v107, 0xffff0000, v107
	v_pk_add_f32 v[164:165], v[164:165], 0 op_sel_hi:[1,0]
	v_pk_add_f32 v[104:105], v[104:105], 0 op_sel_hi:[1,0]
	v_pk_add_f32 v[102:103], v[102:103], v[106:107]
	v_pk_add_f32 v[106:107], v[162:163], v[166:167]
	v_lshlrev_b32_e32 v162, 16, v108
	v_and_b32_e32 v163, 0xffff0000, v108
	v_lshlrev_b32_e32 v108, 16, v109
	v_and_b32_e32 v109, 0xffff0000, v109
	v_pk_add_f32 v[104:105], v[104:105], v[108:109]
	v_pk_add_f32 v[108:109], v[164:165], v[162:163]
	s_waitcnt vmcnt(11)
	v_lshlrev_b32_e32 v162, 16, v110
	v_and_b32_e32 v163, 0xffff0000, v110
	v_lshlrev_b32_e32 v110, 16, v111
	v_and_b32_e32 v111, 0xffff0000, v111
	v_pk_add_f32 v[102:103], v[102:103], v[110:111]
	v_lshlrev_b32_e32 v110, 16, v112
	v_and_b32_e32 v111, 0xffff0000, v112
	v_lshlrev_b32_e32 v112, 16, v113
	v_and_b32_e32 v113, 0xffff0000, v113
	v_pk_add_f32 v[106:107], v[106:107], v[162:163]
	v_pk_add_f32 v[108:109], v[108:109], v[110:111]
	v_pk_add_f32 v[104:105], v[104:105], v[112:113]
	s_waitcnt vmcnt(9)
	v_lshlrev_b32_e32 v110, 16, v114
	v_and_b32_e32 v111, 0xffff0000, v114
	v_lshlrev_b32_e32 v112, 16, v115
	v_and_b32_e32 v113, 0xffff0000, v115
	v_pk_add_f32 v[102:103], v[102:103], v[112:113]
	v_pk_add_f32 v[106:107], v[106:107], v[110:111]
	v_lshlrev_b32_e32 v110, 16, v116
	v_and_b32_e32 v111, 0xffff0000, v116
	v_lshlrev_b32_e32 v112, 16, v117
	v_and_b32_e32 v113, 0xffff0000, v117
	v_pk_add_f32 v[104:105], v[104:105], v[112:113]
	v_pk_add_f32 v[108:109], v[108:109], v[110:111]
	s_waitcnt vmcnt(7)
	v_lshlrev_b32_e32 v110, 16, v118
	v_and_b32_e32 v111, 0xffff0000, v118
	v_lshlrev_b32_e32 v112, 16, v119
	v_and_b32_e32 v113, 0xffff0000, v119
	v_pk_add_f32 v[106:107], v[106:107], v[110:111]
	v_pk_add_f32 v[102:103], v[102:103], v[112:113]
	v_lshlrev_b32_e32 v110, 16, v120
	v_and_b32_e32 v111, 0xffff0000, v120
	v_lshlrev_b32_e32 v112, 16, v121
	v_and_b32_e32 v113, 0xffff0000, v121
	v_pk_add_f32 v[108:109], v[108:109], v[110:111]
	v_pk_add_f32 v[104:105], v[104:105], v[112:113]
	s_waitcnt vmcnt(5)
	v_lshlrev_b32_e32 v110, 16, v122
	v_and_b32_e32 v111, 0xffff0000, v122
	v_lshlrev_b32_e32 v112, 16, v123
	v_and_b32_e32 v113, 0xffff0000, v123
	v_pk_add_f32 v[102:103], v[102:103], v[112:113]
	v_pk_add_f32 v[106:107], v[106:107], v[110:111]
	v_lshlrev_b32_e32 v110, 16, v124
	v_and_b32_e32 v111, 0xffff0000, v124
	v_lshlrev_b32_e32 v112, 16, v125
	v_and_b32_e32 v113, 0xffff0000, v125
	v_pk_add_f32 v[104:105], v[104:105], v[112:113]
	v_pk_add_f32 v[108:109], v[108:109], v[110:111]
	s_waitcnt vmcnt(3)
	v_lshlrev_b32_e32 v110, 16, v126
	v_and_b32_e32 v111, 0xffff0000, v126
	v_lshlrev_b32_e32 v112, 16, v127
	v_and_b32_e32 v113, 0xffff0000, v127
	v_pk_add_f32 v[106:107], v[106:107], v[110:111]
	v_pk_add_f32 v[102:103], v[102:103], v[112:113]
	v_lshlrev_b32_e32 v110, 16, v128
	v_and_b32_e32 v111, 0xffff0000, v128
	v_lshlrev_b32_e32 v112, 16, v129
	v_and_b32_e32 v113, 0xffff0000, v129
	v_pk_add_f32 v[108:109], v[108:109], v[110:111]
	v_pk_add_f32 v[104:105], v[104:105], v[112:113]
	s_waitcnt vmcnt(1)
	v_lshlrev_b32_e32 v110, 16, v156
	v_and_b32_e32 v111, 0xffff0000, v156
	v_lshlrev_b32_e32 v112, 16, v157
	v_and_b32_e32 v113, 0xffff0000, v157
	v_pk_add_f32 v[102:103], v[102:103], v[112:113]
	v_pk_add_f32 v[106:107], v[106:107], v[110:111]
	v_lshlrev_b32_e32 v110, 16, v158
	v_and_b32_e32 v111, 0xffff0000, v158
	v_lshlrev_b32_e32 v112, 16, v159
	v_and_b32_e32 v113, 0xffff0000, v159
	v_pk_add_f32 v[112:113], v[104:105], v[112:113]
	v_pk_add_f32 v[108:109], v[108:109], v[110:111]
	v_cvt_pk_bf16_f32 v105, v102, v103
	v_lshlrev_b64 v[102:103], 12, v[160:161]
	v_cvt_pk_bf16_f32 v104, v106, v107
	v_cvt_pk_bf16_f32 v106, v108, v109
	v_lshl_add_u64 v[108:109], s[40:41], 0, v[102:103]
	v_cvt_pk_bf16_f32 v107, v112, v113
	v_lshl_add_u64 v[108:109], v[146:147], 1, v[108:109]
	global_store_dwordx4 v[108:109], v[104:107], off
	v_lshlrev_b32_e32 v108, 16, v94
	v_and_b32_e32 v109, 0xffff0000, v94
	v_lshlrev_b32_e32 v104, 16, v98
	v_and_b32_e32 v105, 0xffff0000, v98
	v_lshlrev_b32_e32 v98, 16, v99
	v_and_b32_e32 v99, 0xffff0000, v99
	v_pk_add_f32 v[104:105], v[104:105], 0 op_sel_hi:[1,0]
	v_pk_add_f32 v[98:99], v[98:99], 0 op_sel_hi:[1,0]
	v_lshlrev_b32_e32 v106, 16, v100
	v_and_b32_e32 v107, 0xffff0000, v100
	v_lshlrev_b32_e32 v100, 16, v101
	v_and_b32_e32 v101, 0xffff0000, v101
	v_lshlrev_b32_e32 v94, 16, v95
	v_and_b32_e32 v95, 0xffff0000, v95
	v_pk_add_f32 v[106:107], v[106:107], 0 op_sel_hi:[1,0]
	v_pk_add_f32 v[100:101], v[100:101], 0 op_sel_hi:[1,0]
	v_pk_add_f32 v[94:95], v[98:99], v[94:95]
	v_pk_add_f32 v[98:99], v[104:105], v[108:109]
	v_lshlrev_b32_e32 v104, 16, v96
	v_and_b32_e32 v105, 0xffff0000, v96
	v_lshlrev_b32_e32 v96, 16, v97
	v_and_b32_e32 v97, 0xffff0000, v97
	v_pk_add_f32 v[96:97], v[100:101], v[96:97]
	v_pk_add_f32 v[100:101], v[106:107], v[104:105]
	v_lshlrev_b32_e32 v104, 16, v90
	v_and_b32_e32 v105, 0xffff0000, v90
	v_lshlrev_b32_e32 v90, 16, v91
	v_and_b32_e32 v91, 0xffff0000, v91
	v_pk_add_f32 v[90:91], v[94:95], v[90:91]
	v_lshlrev_b32_e32 v94, 16, v92
	v_and_b32_e32 v95, 0xffff0000, v92
	v_lshlrev_b32_e32 v92, 16, v93
	v_and_b32_e32 v93, 0xffff0000, v93
	v_pk_add_f32 v[98:99], v[98:99], v[104:105]
	v_pk_add_f32 v[92:93], v[96:97], v[92:93]
	v_lshlrev_b32_e32 v96, 16, v86
	v_and_b32_e32 v97, 0xffff0000, v86
	v_lshlrev_b32_e32 v86, 16, v87
	v_and_b32_e32 v87, 0xffff0000, v87
	v_pk_add_f32 v[94:95], v[100:101], v[94:95]
	v_pk_add_f32 v[86:87], v[90:91], v[86:87]
	v_pk_add_f32 v[90:91], v[98:99], v[96:97]
	v_lshlrev_b32_e32 v96, 16, v88
	v_and_b32_e32 v97, 0xffff0000, v88
	v_lshlrev_b32_e32 v88, 16, v89
	v_and_b32_e32 v89, 0xffff0000, v89
	v_pk_add_f32 v[88:89], v[92:93], v[88:89]
	v_pk_add_f32 v[92:93], v[94:95], v[96:97]
	v_lshlrev_b32_e32 v94, 16, v82
	v_and_b32_e32 v95, 0xffff0000, v82
	v_lshlrev_b32_e32 v82, 16, v83
	v_and_b32_e32 v83, 0xffff0000, v83
	v_pk_add_f32 v[82:83], v[86:87], v[82:83]
	v_lshlrev_b32_e32 v86, 16, v84
	v_and_b32_e32 v87, 0xffff0000, v84
	v_lshlrev_b32_e32 v84, 16, v85
	v_and_b32_e32 v85, 0xffff0000, v85
	v_pk_add_f32 v[90:91], v[90:91], v[94:95]
	v_pk_add_f32 v[84:85], v[88:89], v[84:85]
	v_lshlrev_b32_e32 v88, 16, v78
	v_and_b32_e32 v89, 0xffff0000, v78
	v_lshlrev_b32_e32 v78, 16, v79
	v_and_b32_e32 v79, 0xffff0000, v79
	v_pk_add_f32 v[86:87], v[92:93], v[86:87]
	v_pk_add_f32 v[78:79], v[82:83], v[78:79]
	v_pk_add_f32 v[82:83], v[90:91], v[88:89]
	v_lshlrev_b32_e32 v88, 16, v80
	v_and_b32_e32 v89, 0xffff0000, v80
	v_lshlrev_b32_e32 v80, 16, v81
	v_and_b32_e32 v81, 0xffff0000, v81
	v_pk_add_f32 v[80:81], v[84:85], v[80:81]
	v_pk_add_f32 v[84:85], v[86:87], v[88:89]
	v_lshlrev_b32_e32 v86, 16, v74
	v_and_b32_e32 v87, 0xffff0000, v74
	v_lshlrev_b32_e32 v74, 16, v75
	v_and_b32_e32 v75, 0xffff0000, v75
	v_pk_add_f32 v[74:75], v[78:79], v[74:75]
	v_lshlrev_b32_e32 v78, 16, v76
	v_and_b32_e32 v79, 0xffff0000, v76
	v_lshlrev_b32_e32 v76, 16, v77
	v_and_b32_e32 v77, 0xffff0000, v77
	v_pk_add_f32 v[78:79], v[84:85], v[78:79]
	s_waitcnt vmcnt(1)
	v_lshlrev_b32_e32 v84, 16, v70
	v_and_b32_e32 v85, 0xffff0000, v70
	v_lshlrev_b32_e32 v70, 16, v71
	v_and_b32_e32 v71, 0xffff0000, v71
	v_pk_add_f32 v[82:83], v[82:83], v[86:87]
	v_pk_add_f32 v[80:81], v[80:81], v[76:77]
	v_pk_add_f32 v[76:77], v[74:75], v[70:71]
	v_lshlrev_b32_e32 v70, 16, v72
	v_and_b32_e32 v71, 0xffff0000, v72
	v_lshlrev_b32_e32 v72, 16, v73
	v_and_b32_e32 v73, 0xffff0000, v73
	v_pk_add_f32 v[74:75], v[82:83], v[84:85]
	v_pk_add_f32 v[72:73], v[80:81], v[72:73]
	v_pk_add_f32 v[70:71], v[78:79], v[70:71]
